# K-loop: per-block setprio flips replaced by one static priority raise for waves 4-7 (strategy 7.4)
# baseline (speedup 1.0000x reference)
.Lfm2_done:
	s_and_b64 vcc, exec, s[80:81]
	s_cbranch_vccnz .Lprio_skip
	s_setprio 1
.Lprio_skip:
	s_add_i32 s34, s19, -2
	s_add_u32 s92, s92, 0x80
	s_addc_u32 s93, s93, 0
	s_add_u32 s96, s94, 0x100
	s_addc_u32 s97, s95, 0
	s_mov_b32 s94, 0
	s_cmp_lt_u32 s59, 2
	s_cbranch_scc1 .Lkloop_zero
	s_add_i32 vcc_lo, s94, 2
	s_add_u32 s82, s92, 0x80
	s_addc_u32 s83, s93, 0
	s_add_i32 vcc_hi, 0, 0x10000
	s_cmp_eq_u32 s34, s94
	s_cselect_b32 s95, s89, s83
	s_cselect_b32 s94, s88, s82
	v_add_u32_e32 v136, vcc_hi, v176
	s_cselect_b32 s83, s91, s97
	s_cselect_b32 s82, s90, s96
	s_add_i32 s7, 0, 0x14000
	s_waitcnt lgkmcnt(0)
	ds_read_b128 v[128:131], v136
	ds_read_b128 v[132:135], v136 offset:1024
	ds_read_b128 v[152:155], v136 offset:2048
	ds_read_b128 v[156:159], v136 offset:3072
	v_add_u32_e32 v136, s7, v176
	ds_read_b128 v[180:183], v136
	ds_read_b128 v[184:187], v136 offset:1024
	ds_read_b128 v[188:191], v136 offset:2048
	ds_read_b128 v[192:195], v136 offset:3072
	v_lshl_add_u64 v[160:161], s[92:93], 0, v[148:149]
	s_add_i32 m0, s52, 0xc000
	ds_read_b128 v[196:199], v178
	ds_read_b128 v[200:203], v178 offset:1024
	ds_read_b128 v[204:207], v178 offset:2048
	ds_read_b128 v[208:211], v178 offset:3072
	ds_read_b128 v[212:215], v178 offset:4096
	ds_read_b128 v[216:219], v178 offset:5120
	ds_read_b128 v[220:223], v178 offset:6144
	ds_read_b128 v[224:227], v178 offset:7168
	global_load_lds_dwordx4 v[160:161], off
	v_lshl_add_u64 v[160:161], s[92:93], 0, v[150:151]
	s_add_i32 m0, s52, 0xe000
	s_nop 0
	global_load_lds_dwordx4 v[160:161], off
	s_waitcnt vmcnt(24)
	s_waitcnt lgkmcnt(0)
	s_barrier
	s_waitcnt lgkmcnt(0)
	v_mfma_f32_16x16x32_bf16 v[124:127], v[128:131], v[196:199], 0
	v_mfma_f32_16x16x32_bf16 v[120:123], v[152:155], v[196:199], 0
	v_mfma_f32_16x16x32_bf16 v[108:111], v[128:131], v[204:207], 0
	v_mfma_f32_16x16x32_bf16 v[104:107], v[152:155], v[204:207], 0
	v_mfma_f32_16x16x32_bf16 v[92:95], v[128:131], v[212:215], 0
	v_mfma_f32_16x16x32_bf16 v[88:91], v[152:155], v[212:215], 0
	v_mfma_f32_16x16x32_bf16 v[76:79], v[128:131], v[220:223], 0
	v_mfma_f32_16x16x32_bf16 v[72:75], v[152:155], v[220:223], 0
	v_mfma_f32_16x16x32_bf16 v[124:127], v[132:135], v[200:203], v[124:127]
	v_mfma_f32_16x16x32_bf16 v[120:123], v[156:159], v[200:203], v[120:123]
	v_mfma_f32_16x16x32_bf16 v[108:111], v[132:135], v[208:211], v[108:111]
	v_mfma_f32_16x16x32_bf16 v[104:107], v[156:159], v[208:211], v[104:107]
	v_mfma_f32_16x16x32_bf16 v[92:95], v[132:135], v[216:219], v[92:95]
	v_mfma_f32_16x16x32_bf16 v[88:91], v[156:159], v[216:219], v[88:91]
	v_mfma_f32_16x16x32_bf16 v[76:79], v[132:135], v[224:227], v[76:79]
	v_mfma_f32_16x16x32_bf16 v[72:75], v[156:159], v[224:227], v[72:75]
	v_mfma_f32_16x16x32_bf16 v[116:119], v[180:183], v[196:199], 0
	v_mfma_f32_16x16x32_bf16 v[112:115], v[188:191], v[196:199], 0
	v_mfma_f32_16x16x32_bf16 v[100:103], v[180:183], v[204:207], 0
	v_mfma_f32_16x16x32_bf16 v[96:99], v[188:191], v[204:207], 0
	v_mfma_f32_16x16x32_bf16 v[84:87], v[180:183], v[212:215], 0
	v_mfma_f32_16x16x32_bf16 v[80:83], v[188:191], v[212:215], 0
	v_mfma_f32_16x16x32_bf16 v[68:71], v[180:183], v[220:223], 0
	v_mfma_f32_16x16x32_bf16 v[64:67], v[188:191], v[220:223], 0
	v_mfma_f32_16x16x32_bf16 v[116:119], v[184:187], v[200:203], v[116:119]
	v_mfma_f32_16x16x32_bf16 v[112:115], v[192:195], v[200:203], v[112:115]
	v_mfma_f32_16x16x32_bf16 v[100:103], v[184:187], v[208:211], v[100:103]
	v_mfma_f32_16x16x32_bf16 v[96:99], v[192:195], v[208:211], v[96:99]
	v_mfma_f32_16x16x32_bf16 v[84:87], v[184:187], v[216:219], v[84:87]
	v_mfma_f32_16x16x32_bf16 v[80:83], v[192:195], v[216:219], v[80:83]
	v_mfma_f32_16x16x32_bf16 v[68:71], v[184:187], v[224:227], v[68:71]
	v_mfma_f32_16x16x32_bf16 v[64:67], v[192:195], v[224:227], v[64:67]
	s_barrier
	s_add_i32 vcc_hi, vcc_hi, s51
	v_lshl_add_u64 v[160:161], s[82:83], 0, v[140:141]
	s_mov_b32 m0, vcc_hi
	ds_read_b128 v[196:199], v178 offset:16384
	ds_read_b128 v[200:203], v178 offset:17408
	ds_read_b128 v[204:207], v178 offset:18432
	ds_read_b128 v[208:211], v178 offset:19456
	ds_read_b128 v[212:215], v178 offset:20480
	ds_read_b128 v[216:219], v178 offset:21504
	ds_read_b128 v[220:223], v178 offset:22528
	ds_read_b128 v[224:227], v178 offset:23552
	global_load_lds_dwordx4 v[160:161], off
	s_add_i32 m0, vcc_hi, 0x2000
	v_lshl_add_u64 v[228:229], s[82:83], 0, v[144:145]
	s_add_u32 s82, s82, s2
	s_addc_u32 s83, s83, s3
	s_add_i32 s7, s7, s51
	global_load_lds_dwordx4 v[228:229], off
	v_lshl_add_u64 v[230:231], s[82:83], 0, v[140:141]
	s_mov_b32 m0, s7
	v_lshl_add_u64 v[232:233], s[82:83], 0, v[144:145]
	global_load_lds_dwordx4 v[230:231], off
	s_add_i32 m0, s7, 0x2000
	v_lshl_add_u64 v[234:235], s[94:95], 0, v[138:139]
	global_load_lds_dwordx4 v[232:233], off
	s_mov_b32 m0, s52
	v_lshl_add_u64 v[236:237], s[94:95], 0, v[142:143]
	global_load_lds_dwordx4 v[234:235], off
	s_mov_b32 m0, s53
	s_nop 0
	global_load_lds_dwordx4 v[236:237], off
	s_waitcnt vmcnt(24)
	s_waitcnt lgkmcnt(0)
	s_barrier
	s_waitcnt lgkmcnt(0)
	v_mfma_f32_16x16x32_bf16 v[60:63], v[128:131], v[196:199], 0
	v_mfma_f32_16x16x32_bf16 v[56:59], v[152:155], v[196:199], 0
	v_mfma_f32_16x16x32_bf16 v[44:47], v[128:131], v[204:207], 0
	v_mfma_f32_16x16x32_bf16 v[40:43], v[152:155], v[204:207], 0
	v_mfma_f32_16x16x32_bf16 v[28:31], v[128:131], v[212:215], 0
	v_mfma_f32_16x16x32_bf16 v[24:27], v[152:155], v[212:215], 0
	v_mfma_f32_16x16x32_bf16 v[12:15], v[128:131], v[220:223], 0
	v_mfma_f32_16x16x32_bf16 v[8:11], v[152:155], v[220:223], 0
	v_mfma_f32_16x16x32_bf16 v[60:63], v[132:135], v[200:203], v[60:63]
	v_mfma_f32_16x16x32_bf16 v[56:59], v[156:159], v[200:203], v[56:59]
	v_mfma_f32_16x16x32_bf16 v[44:47], v[132:135], v[208:211], v[44:47]
	v_mfma_f32_16x16x32_bf16 v[40:43], v[156:159], v[208:211], v[40:43]
	v_mfma_f32_16x16x32_bf16 v[28:31], v[132:135], v[216:219], v[28:31]
	v_mfma_f32_16x16x32_bf16 v[24:27], v[156:159], v[216:219], v[24:27]
	v_mfma_f32_16x16x32_bf16 v[12:15], v[132:135], v[224:227], v[12:15]
	v_mfma_f32_16x16x32_bf16 v[8:11], v[156:159], v[224:227], v[8:11]
	v_mfma_f32_16x16x32_bf16 v[52:55], v[180:183], v[196:199], 0
	v_mfma_f32_16x16x32_bf16 v[48:51], v[188:191], v[196:199], 0
	v_mfma_f32_16x16x32_bf16 v[36:39], v[180:183], v[204:207], 0
	v_mfma_f32_16x16x32_bf16 v[32:35], v[188:191], v[204:207], 0
	v_mfma_f32_16x16x32_bf16 v[20:23], v[180:183], v[212:215], 0
	v_mfma_f32_16x16x32_bf16 v[16:19], v[188:191], v[212:215], 0
	v_mfma_f32_16x16x32_bf16 v[4:7], v[180:183], v[220:223], 0
	v_mfma_f32_16x16x32_bf16 v[0:3], v[188:191], v[220:223], 0
	v_mfma_f32_16x16x32_bf16 v[52:55], v[184:187], v[200:203], v[52:55]
	v_mfma_f32_16x16x32_bf16 v[48:51], v[192:195], v[200:203], v[48:51]
	v_mfma_f32_16x16x32_bf16 v[36:39], v[184:187], v[208:211], v[36:39]
	v_mfma_f32_16x16x32_bf16 v[32:35], v[192:195], v[208:211], v[32:35]
	v_mfma_f32_16x16x32_bf16 v[20:23], v[184:187], v[216:219], v[20:23]
	v_mfma_f32_16x16x32_bf16 v[16:19], v[192:195], v[216:219], v[16:19]
	v_mfma_f32_16x16x32_bf16 v[4:7], v[184:187], v[224:227], v[4:7]
	v_mfma_f32_16x16x32_bf16 v[0:3], v[192:195], v[224:227], v[0:3]
	s_barrier
	s_add_i32 s7, 0, 0x18000
	v_add_u32_e32 v136, s7, v176
	s_add_i32 vcc_hi, 0, 0x1c000
	ds_read_b128 v[128:131], v136
	ds_read_b128 v[132:135], v136 offset:1024
	ds_read_b128 v[152:155], v136 offset:2048
	ds_read_b128 v[156:159], v136 offset:3072
	v_add_u32_e32 v136, vcc_hi, v176
	ds_read_b128 v[180:183], v136
	ds_read_b128 v[184:187], v136 offset:1024
	ds_read_b128 v[188:191], v136 offset:2048
	ds_read_b128 v[192:195], v136 offset:3072
	s_add_u32 s82, s94, s2
	s_addc_u32 s83, s95, s3
	s_mov_b32 m0, s54
	v_lshl_add_u64 v[238:239], s[82:83], 0, v[138:139]
	ds_read_b128 v[196:199], v178 offset:32768
	ds_read_b128 v[200:203], v178 offset:33792
	ds_read_b128 v[204:207], v178 offset:34816
	ds_read_b128 v[208:211], v178 offset:35840
	ds_read_b128 v[212:215], v178 offset:36864
	ds_read_b128 v[216:219], v178 offset:37888
	ds_read_b128 v[220:223], v178 offset:38912
	ds_read_b128 v[224:227], v178 offset:39936
	global_load_lds_dwordx4 v[238:239], off
	v_lshl_add_u64 v[238:239], s[82:83], 0, v[142:143]
	s_mov_b32 m0, s55
	s_nop 0
	global_load_lds_dwordx4 v[238:239], off
	s_waitcnt vmcnt(8)
	s_waitcnt lgkmcnt(0)
	s_barrier
	s_waitcnt lgkmcnt(0)
	v_mfma_f32_16x16x32_bf16 v[124:127], v[128:131], v[196:199], v[124:127]
	v_mfma_f32_16x16x32_bf16 v[120:123], v[152:155], v[196:199], v[120:123]
	v_mfma_f32_16x16x32_bf16 v[108:111], v[128:131], v[204:207], v[108:111]
	v_mfma_f32_16x16x32_bf16 v[104:107], v[152:155], v[204:207], v[104:107]
	v_mfma_f32_16x16x32_bf16 v[92:95], v[128:131], v[212:215], v[92:95]
	v_mfma_f32_16x16x32_bf16 v[88:91], v[152:155], v[212:215], v[88:91]
	v_mfma_f32_16x16x32_bf16 v[76:79], v[128:131], v[220:223], v[76:79]
	v_mfma_f32_16x16x32_bf16 v[72:75], v[152:155], v[220:223], v[72:75]
	v_mfma_f32_16x16x32_bf16 v[124:127], v[132:135], v[200:203], v[124:127]
	v_mfma_f32_16x16x32_bf16 v[120:123], v[156:159], v[200:203], v[120:123]
	v_mfma_f32_16x16x32_bf16 v[108:111], v[132:135], v[208:211], v[108:111]
	v_mfma_f32_16x16x32_bf16 v[104:107], v[156:159], v[208:211], v[104:107]
	v_mfma_f32_16x16x32_bf16 v[92:95], v[132:135], v[216:219], v[92:95]
	v_mfma_f32_16x16x32_bf16 v[88:91], v[156:159], v[216:219], v[88:91]
	v_mfma_f32_16x16x32_bf16 v[76:79], v[132:135], v[224:227], v[76:79]
	v_mfma_f32_16x16x32_bf16 v[72:75], v[156:159], v[224:227], v[72:75]
	v_mfma_f32_16x16x32_bf16 v[116:119], v[180:183], v[196:199], v[116:119]
	v_mfma_f32_16x16x32_bf16 v[112:115], v[188:191], v[196:199], v[112:115]
	v_mfma_f32_16x16x32_bf16 v[100:103], v[180:183], v[204:207], v[100:103]
	v_mfma_f32_16x16x32_bf16 v[96:99], v[188:191], v[204:207], v[96:99]
	v_mfma_f32_16x16x32_bf16 v[84:87], v[180:183], v[212:215], v[84:87]
	v_mfma_f32_16x16x32_bf16 v[80:83], v[188:191], v[212:215], v[80:83]
	v_mfma_f32_16x16x32_bf16 v[68:71], v[180:183], v[220:223], v[68:71]
	v_mfma_f32_16x16x32_bf16 v[64:67], v[188:191], v[220:223], v[64:67]
	v_mfma_f32_16x16x32_bf16 v[116:119], v[184:187], v[200:203], v[116:119]
	v_mfma_f32_16x16x32_bf16 v[112:115], v[192:195], v[200:203], v[112:115]
	v_mfma_f32_16x16x32_bf16 v[100:103], v[184:187], v[208:211], v[100:103]
	v_mfma_f32_16x16x32_bf16 v[96:99], v[192:195], v[208:211], v[96:99]
	v_mfma_f32_16x16x32_bf16 v[84:87], v[184:187], v[216:219], v[84:87]
	v_mfma_f32_16x16x32_bf16 v[80:83], v[192:195], v[216:219], v[80:83]
	v_mfma_f32_16x16x32_bf16 v[68:71], v[184:187], v[224:227], v[68:71]
	v_mfma_f32_16x16x32_bf16 v[64:67], v[192:195], v[224:227], v[64:67]
	s_barrier
	s_add_i32 s7, s7, s51
	v_lshl_add_u64 v[160:161], v[160:161], 0, s[26:27]
	s_mov_b32 m0, s7
	ds_read_b128 v[196:199], v178 offset:49152
	ds_read_b128 v[200:203], v178 offset:50176
	ds_read_b128 v[204:207], v178 offset:51200
	ds_read_b128 v[208:211], v178 offset:52224
	ds_read_b128 v[212:215], v178 offset:53248
	ds_read_b128 v[216:219], v178 offset:54272
	ds_read_b128 v[220:223], v178 offset:55296
	ds_read_b128 v[224:227], v178 offset:56320
	global_load_lds_dwordx4 v[160:161], off
	v_lshl_add_u64 v[160:161], v[228:229], 0, s[26:27]
	s_add_i32 m0, s7, 0x2000
	s_add_i32 s7, vcc_hi, s51
	global_load_lds_dwordx4 v[160:161], off
	v_lshl_add_u64 v[160:161], v[230:231], 0, s[26:27]
	s_mov_b32 m0, s7
	s_nop 0
	global_load_lds_dwordx4 v[160:161], off
	v_lshl_add_u64 v[160:161], v[232:233], 0, s[26:27]
	s_add_i32 m0, s7, 0x2000
	s_nop 0
	global_load_lds_dwordx4 v[160:161], off
	v_lshl_add_u64 v[160:161], v[234:235], 0, s[26:27]
	s_mov_b32 m0, s57
	s_nop 0
	global_load_lds_dwordx4 v[160:161], off
	v_lshl_add_u64 v[160:161], v[236:237], 0, s[26:27]
	s_mov_b32 m0, s58
	s_nop 0
	global_load_lds_dwordx4 v[160:161], off
	s_waitcnt vmcnt(8)
	s_waitcnt lgkmcnt(0)
	s_barrier
	s_waitcnt lgkmcnt(0)
	v_mfma_f32_16x16x32_bf16 v[60:63], v[128:131], v[196:199], v[60:63]
	v_mfma_f32_16x16x32_bf16 v[56:59], v[152:155], v[196:199], v[56:59]
	v_mfma_f32_16x16x32_bf16 v[44:47], v[128:131], v[204:207], v[44:47]
	v_mfma_f32_16x16x32_bf16 v[40:43], v[152:155], v[204:207], v[40:43]
	v_mfma_f32_16x16x32_bf16 v[28:31], v[128:131], v[212:215], v[28:31]
	v_mfma_f32_16x16x32_bf16 v[24:27], v[152:155], v[212:215], v[24:27]
	v_mfma_f32_16x16x32_bf16 v[12:15], v[128:131], v[220:223], v[12:15]
	v_mfma_f32_16x16x32_bf16 v[8:11], v[152:155], v[220:223], v[8:11]
	v_mfma_f32_16x16x32_bf16 v[60:63], v[132:135], v[200:203], v[60:63]
	v_mfma_f32_16x16x32_bf16 v[56:59], v[156:159], v[200:203], v[56:59]
	v_mfma_f32_16x16x32_bf16 v[44:47], v[132:135], v[208:211], v[44:47]
	v_mfma_f32_16x16x32_bf16 v[40:43], v[156:159], v[208:211], v[40:43]
	v_mfma_f32_16x16x32_bf16 v[28:31], v[132:135], v[216:219], v[28:31]
	v_mfma_f32_16x16x32_bf16 v[24:27], v[156:159], v[216:219], v[24:27]
	v_mfma_f32_16x16x32_bf16 v[12:15], v[132:135], v[224:227], v[12:15]
	v_mfma_f32_16x16x32_bf16 v[8:11], v[156:159], v[224:227], v[8:11]
	v_mfma_f32_16x16x32_bf16 v[52:55], v[180:183], v[196:199], v[52:55]
	v_mfma_f32_16x16x32_bf16 v[48:51], v[188:191], v[196:199], v[48:51]
	v_mfma_f32_16x16x32_bf16 v[36:39], v[180:183], v[204:207], v[36:39]
	v_mfma_f32_16x16x32_bf16 v[32:35], v[188:191], v[204:207], v[32:35]
	v_mfma_f32_16x16x32_bf16 v[20:23], v[180:183], v[212:215], v[20:23]
	v_mfma_f32_16x16x32_bf16 v[16:19], v[188:191], v[212:215], v[16:19]
	v_mfma_f32_16x16x32_bf16 v[4:7], v[180:183], v[220:223], v[4:7]
	v_mfma_f32_16x16x32_bf16 v[0:3], v[188:191], v[220:223], v[0:3]
	v_mfma_f32_16x16x32_bf16 v[52:55], v[184:187], v[200:203], v[52:55]
	v_mfma_f32_16x16x32_bf16 v[48:51], v[192:195], v[200:203], v[48:51]
	v_mfma_f32_16x16x32_bf16 v[36:39], v[184:187], v[208:211], v[36:39]
	v_mfma_f32_16x16x32_bf16 v[32:35], v[192:195], v[208:211], v[32:35]
	v_mfma_f32_16x16x32_bf16 v[20:23], v[184:187], v[216:219], v[20:23]
	v_mfma_f32_16x16x32_bf16 v[16:19], v[192:195], v[216:219], v[16:19]
	v_mfma_f32_16x16x32_bf16 v[4:7], v[184:187], v[224:227], v[4:7]
	v_mfma_f32_16x16x32_bf16 v[0:3], v[192:195], v[224:227], v[0:3]
	s_barrier
	s_add_u32 s92, s92, 0x100
	s_addc_u32 s93, s93, 0
	s_add_u32 s96, s96, 0x100
	s_addc_u32 s97, s97, 0
	s_cmp_ge_u32 vcc_lo, s19
	s_mov_b32 s94, vcc_lo
	s_cbranch_scc0 .LBB0_150
	s_branch .Lkloop_done

.LBB0_150:
	s_add_i32 vcc_lo, s94, 2
	s_add_u32 s82, s92, 0x80
	s_addc_u32 s83, s93, 0
	s_add_i32 vcc_hi, 0, 0x10000
	s_cmp_eq_u32 s34, s94
	s_cselect_b32 s95, s89, s83
	s_cselect_b32 s94, s88, s82
	v_add_u32_e32 v136, vcc_hi, v176
	s_cselect_b32 s83, s91, s97
	s_cselect_b32 s82, s90, s96
	s_add_i32 s7, 0, 0x14000
	s_waitcnt lgkmcnt(0)
	ds_read_b128 v[128:131], v136
	ds_read_b128 v[132:135], v136 offset:1024
	ds_read_b128 v[152:155], v136 offset:2048
	ds_read_b128 v[156:159], v136 offset:3072
	v_add_u32_e32 v136, s7, v176
	ds_read_b128 v[180:183], v136
	ds_read_b128 v[184:187], v136 offset:1024
	ds_read_b128 v[188:191], v136 offset:2048
	ds_read_b128 v[192:195], v136 offset:3072
	v_lshl_add_u64 v[160:161], s[92:93], 0, v[148:149]
	s_add_i32 m0, s52, 0xc000
	ds_read_b128 v[196:199], v178
	ds_read_b128 v[200:203], v178 offset:1024
	ds_read_b128 v[204:207], v178 offset:2048
	ds_read_b128 v[208:211], v178 offset:3072
	ds_read_b128 v[212:215], v178 offset:4096
	ds_read_b128 v[216:219], v178 offset:5120
	ds_read_b128 v[220:223], v178 offset:6144
	ds_read_b128 v[224:227], v178 offset:7168
	global_load_lds_dwordx4 v[160:161], off
	v_lshl_add_u64 v[160:161], s[92:93], 0, v[150:151]
	s_add_i32 m0, s52, 0xe000
	s_nop 0
	global_load_lds_dwordx4 v[160:161], off
	s_waitcnt vmcnt(8)
	s_waitcnt lgkmcnt(0)
	s_barrier
	s_waitcnt lgkmcnt(0)
	v_mfma_f32_16x16x32_bf16 v[124:127], v[128:131], v[196:199], v[124:127]
	v_mfma_f32_16x16x32_bf16 v[120:123], v[152:155], v[196:199], v[120:123]
	v_mfma_f32_16x16x32_bf16 v[108:111], v[128:131], v[204:207], v[108:111]
	v_mfma_f32_16x16x32_bf16 v[104:107], v[152:155], v[204:207], v[104:107]
	v_mfma_f32_16x16x32_bf16 v[92:95], v[128:131], v[212:215], v[92:95]
	v_mfma_f32_16x16x32_bf16 v[88:91], v[152:155], v[212:215], v[88:91]
	v_mfma_f32_16x16x32_bf16 v[76:79], v[128:131], v[220:223], v[76:79]
	v_mfma_f32_16x16x32_bf16 v[72:75], v[152:155], v[220:223], v[72:75]
	v_mfma_f32_16x16x32_bf16 v[124:127], v[132:135], v[200:203], v[124:127]
	v_mfma_f32_16x16x32_bf16 v[120:123], v[156:159], v[200:203], v[120:123]
	v_mfma_f32_16x16x32_bf16 v[108:111], v[132:135], v[208:211], v[108:111]
	v_mfma_f32_16x16x32_bf16 v[104:107], v[156:159], v[208:211], v[104:107]
	v_mfma_f32_16x16x32_bf16 v[92:95], v[132:135], v[216:219], v[92:95]
	v_mfma_f32_16x16x32_bf16 v[88:91], v[156:159], v[216:219], v[88:91]
	v_mfma_f32_16x16x32_bf16 v[76:79], v[132:135], v[224:227], v[76:79]
	v_mfma_f32_16x16x32_bf16 v[72:75], v[156:159], v[224:227], v[72:75]
	v_mfma_f32_16x16x32_bf16 v[116:119], v[180:183], v[196:199], v[116:119]
	v_mfma_f32_16x16x32_bf16 v[112:115], v[188:191], v[196:199], v[112:115]
	v_mfma_f32_16x16x32_bf16 v[100:103], v[180:183], v[204:207], v[100:103]
	v_mfma_f32_16x16x32_bf16 v[96:99], v[188:191], v[204:207], v[96:99]
	v_mfma_f32_16x16x32_bf16 v[84:87], v[180:183], v[212:215], v[84:87]
	v_mfma_f32_16x16x32_bf16 v[80:83], v[188:191], v[212:215], v[80:83]
	v_mfma_f32_16x16x32_bf16 v[68:71], v[180:183], v[220:223], v[68:71]
	v_mfma_f32_16x16x32_bf16 v[64:67], v[188:191], v[220:223], v[64:67]
	v_mfma_f32_16x16x32_bf16 v[116:119], v[184:187], v[200:203], v[116:119]
	v_mfma_f32_16x16x32_bf16 v[112:115], v[192:195], v[200:203], v[112:115]
	v_mfma_f32_16x16x32_bf16 v[100:103], v[184:187], v[208:211], v[100:103]
	v_mfma_f32_16x16x32_bf16 v[96:99], v[192:195], v[208:211], v[96:99]
	v_mfma_f32_16x16x32_bf16 v[84:87], v[184:187], v[216:219], v[84:87]
	v_mfma_f32_16x16x32_bf16 v[80:83], v[192:195], v[216:219], v[80:83]
	v_mfma_f32_16x16x32_bf16 v[68:71], v[184:187], v[224:227], v[68:71]
	v_mfma_f32_16x16x32_bf16 v[64:67], v[192:195], v[224:227], v[64:67]
	s_barrier
	s_add_i32 vcc_hi, vcc_hi, s51
	v_lshl_add_u64 v[160:161], s[82:83], 0, v[140:141]
	s_mov_b32 m0, vcc_hi
	ds_read_b128 v[196:199], v178 offset:16384
	ds_read_b128 v[200:203], v178 offset:17408
	ds_read_b128 v[204:207], v178 offset:18432
	ds_read_b128 v[208:211], v178 offset:19456
	ds_read_b128 v[212:215], v178 offset:20480
	ds_read_b128 v[216:219], v178 offset:21504
	ds_read_b128 v[220:223], v178 offset:22528
	ds_read_b128 v[224:227], v178 offset:23552
	global_load_lds_dwordx4 v[160:161], off
	s_add_i32 m0, vcc_hi, 0x2000
	v_lshl_add_u64 v[228:229], s[82:83], 0, v[144:145]
	s_add_u32 s82, s82, s2
	s_addc_u32 s83, s83, s3
	s_add_i32 s7, s7, s51
	global_load_lds_dwordx4 v[228:229], off
	v_lshl_add_u64 v[230:231], s[82:83], 0, v[140:141]
	s_mov_b32 m0, s7
	v_lshl_add_u64 v[232:233], s[82:83], 0, v[144:145]
	global_load_lds_dwordx4 v[230:231], off
	s_add_i32 m0, s7, 0x2000
	v_lshl_add_u64 v[234:235], s[94:95], 0, v[138:139]
	global_load_lds_dwordx4 v[232:233], off
	s_mov_b32 m0, s52
	v_lshl_add_u64 v[236:237], s[94:95], 0, v[142:143]
	global_load_lds_dwordx4 v[234:235], off
	s_mov_b32 m0, s53
	s_nop 0
	global_load_lds_dwordx4 v[236:237], off
	s_waitcnt vmcnt(8)
	s_waitcnt lgkmcnt(0)
	s_barrier
	s_waitcnt lgkmcnt(0)
	v_mfma_f32_16x16x32_bf16 v[60:63], v[128:131], v[196:199], v[60:63]
	v_mfma_f32_16x16x32_bf16 v[56:59], v[152:155], v[196:199], v[56:59]
	v_mfma_f32_16x16x32_bf16 v[44:47], v[128:131], v[204:207], v[44:47]
	v_mfma_f32_16x16x32_bf16 v[40:43], v[152:155], v[204:207], v[40:43]
	v_mfma_f32_16x16x32_bf16 v[28:31], v[128:131], v[212:215], v[28:31]
	v_mfma_f32_16x16x32_bf16 v[24:27], v[152:155], v[212:215], v[24:27]
	v_mfma_f32_16x16x32_bf16 v[12:15], v[128:131], v[220:223], v[12:15]
	v_mfma_f32_16x16x32_bf16 v[8:11], v[152:155], v[220:223], v[8:11]
	v_mfma_f32_16x16x32_bf16 v[60:63], v[132:135], v[200:203], v[60:63]
	v_mfma_f32_16x16x32_bf16 v[56:59], v[156:159], v[200:203], v[56:59]
	v_mfma_f32_16x16x32_bf16 v[44:47], v[132:135], v[208:211], v[44:47]
	v_mfma_f32_16x16x32_bf16 v[40:43], v[156:159], v[208:211], v[40:43]
	v_mfma_f32_16x16x32_bf16 v[28:31], v[132:135], v[216:219], v[28:31]
	v_mfma_f32_16x16x32_bf16 v[24:27], v[156:159], v[216:219], v[24:27]
	v_mfma_f32_16x16x32_bf16 v[12:15], v[132:135], v[224:227], v[12:15]
	v_mfma_f32_16x16x32_bf16 v[8:11], v[156:159], v[224:227], v[8:11]
	v_mfma_f32_16x16x32_bf16 v[52:55], v[180:183], v[196:199], v[52:55]
	v_mfma_f32_16x16x32_bf16 v[48:51], v[188:191], v[196:199], v[48:51]
	v_mfma_f32_16x16x32_bf16 v[36:39], v[180:183], v[204:207], v[36:39]
	v_mfma_f32_16x16x32_bf16 v[32:35], v[188:191], v[204:207], v[32:35]
	v_mfma_f32_16x16x32_bf16 v[20:23], v[180:183], v[212:215], v[20:23]
	v_mfma_f32_16x16x32_bf16 v[16:19], v[188:191], v[212:215], v[16:19]
	v_mfma_f32_16x16x32_bf16 v[4:7], v[180:183], v[220:223], v[4:7]
	v_mfma_f32_16x16x32_bf16 v[0:3], v[188:191], v[220:223], v[0:3]
	v_mfma_f32_16x16x32_bf16 v[52:55], v[184:187], v[200:203], v[52:55]
	v_mfma_f32_16x16x32_bf16 v[48:51], v[192:195], v[200:203], v[48:51]
	v_mfma_f32_16x16x32_bf16 v[36:39], v[184:187], v[208:211], v[36:39]
	v_mfma_f32_16x16x32_bf16 v[32:35], v[192:195], v[208:211], v[32:35]
	v_mfma_f32_16x16x32_bf16 v[20:23], v[184:187], v[216:219], v[20:23]
	v_mfma_f32_16x16x32_bf16 v[16:19], v[192:195], v[216:219], v[16:19]
	v_mfma_f32_16x16x32_bf16 v[4:7], v[184:187], v[224:227], v[4:7]
	v_mfma_f32_16x16x32_bf16 v[0:3], v[192:195], v[224:227], v[0:3]
	s_barrier
	s_add_i32 s7, 0, 0x18000
	v_add_u32_e32 v136, s7, v176
	s_add_i32 vcc_hi, 0, 0x1c000
	ds_read_b128 v[128:131], v136
	ds_read_b128 v[132:135], v136 offset:1024
	ds_read_b128 v[152:155], v136 offset:2048
	ds_read_b128 v[156:159], v136 offset:3072
	v_add_u32_e32 v136, vcc_hi, v176
	ds_read_b128 v[180:183], v136
	ds_read_b128 v[184:187], v136 offset:1024
	ds_read_b128 v[188:191], v136 offset:2048
	ds_read_b128 v[192:195], v136 offset:3072
	s_add_u32 s82, s94, s2
	s_addc_u32 s83, s95, s3
	s_mov_b32 m0, s54
	v_lshl_add_u64 v[238:239], s[82:83], 0, v[138:139]
	ds_read_b128 v[196:199], v178 offset:32768
	ds_read_b128 v[200:203], v178 offset:33792
	ds_read_b128 v[204:207], v178 offset:34816
	ds_read_b128 v[208:211], v178 offset:35840
	ds_read_b128 v[212:215], v178 offset:36864
	ds_read_b128 v[216:219], v178 offset:37888
	ds_read_b128 v[220:223], v178 offset:38912
	ds_read_b128 v[224:227], v178 offset:39936
	global_load_lds_dwordx4 v[238:239], off
	v_lshl_add_u64 v[238:239], s[82:83], 0, v[142:143]
	s_mov_b32 m0, s55
	s_nop 0
	global_load_lds_dwordx4 v[238:239], off
	s_waitcnt vmcnt(8)
	s_waitcnt lgkmcnt(0)
	s_barrier
	s_waitcnt lgkmcnt(0)
	v_mfma_f32_16x16x32_bf16 v[124:127], v[128:131], v[196:199], v[124:127]
	v_mfma_f32_16x16x32_bf16 v[120:123], v[152:155], v[196:199], v[120:123]
	v_mfma_f32_16x16x32_bf16 v[108:111], v[128:131], v[204:207], v[108:111]
	v_mfma_f32_16x16x32_bf16 v[104:107], v[152:155], v[204:207], v[104:107]
	v_mfma_f32_16x16x32_bf16 v[92:95], v[128:131], v[212:215], v[92:95]
	v_mfma_f32_16x16x32_bf16 v[88:91], v[152:155], v[212:215], v[88:91]
	v_mfma_f32_16x16x32_bf16 v[76:79], v[128:131], v[220:223], v[76:79]
	v_mfma_f32_16x16x32_bf16 v[72:75], v[152:155], v[220:223], v[72:75]
	v_mfma_f32_16x16x32_bf16 v[124:127], v[132:135], v[200:203], v[124:127]
	v_mfma_f32_16x16x32_bf16 v[120:123], v[156:159], v[200:203], v[120:123]
	v_mfma_f32_16x16x32_bf16 v[108:111], v[132:135], v[208:211], v[108:111]
	v_mfma_f32_16x16x32_bf16 v[104:107], v[156:159], v[208:211], v[104:107]
	v_mfma_f32_16x16x32_bf16 v[92:95], v[132:135], v[216:219], v[92:95]
	v_mfma_f32_16x16x32_bf16 v[88:91], v[156:159], v[216:219], v[88:91]
	v_mfma_f32_16x16x32_bf16 v[76:79], v[132:135], v[224:227], v[76:79]
	v_mfma_f32_16x16x32_bf16 v[72:75], v[156:159], v[224:227], v[72:75]
	v_mfma_f32_16x16x32_bf16 v[116:119], v[180:183], v[196:199], v[116:119]
	v_mfma_f32_16x16x32_bf16 v[112:115], v[188:191], v[196:199], v[112:115]
	v_mfma_f32_16x16x32_bf16 v[100:103], v[180:183], v[204:207], v[100:103]
	v_mfma_f32_16x16x32_bf16 v[96:99], v[188:191], v[204:207], v[96:99]
	v_mfma_f32_16x16x32_bf16 v[84:87], v[180:183], v[212:215], v[84:87]
	v_mfma_f32_16x16x32_bf16 v[80:83], v[188:191], v[212:215], v[80:83]
	v_mfma_f32_16x16x32_bf16 v[68:71], v[180:183], v[220:223], v[68:71]
	v_mfma_f32_16x16x32_bf16 v[64:67], v[188:191], v[220:223], v[64:67]
	v_mfma_f32_16x16x32_bf16 v[116:119], v[184:187], v[200:203], v[116:119]
	v_mfma_f32_16x16x32_bf16 v[112:115], v[192:195], v[200:203], v[112:115]
	v_mfma_f32_16x16x32_bf16 v[100:103], v[184:187], v[208:211], v[100:103]
	v_mfma_f32_16x16x32_bf16 v[96:99], v[192:195], v[208:211], v[96:99]
	v_mfma_f32_16x16x32_bf16 v[84:87], v[184:187], v[216:219], v[84:87]
	v_mfma_f32_16x16x32_bf16 v[80:83], v[192:195], v[216:219], v[80:83]
	v_mfma_f32_16x16x32_bf16 v[68:71], v[184:187], v[224:227], v[68:71]
	v_mfma_f32_16x16x32_bf16 v[64:67], v[192:195], v[224:227], v[64:67]
	s_barrier
	s_add_i32 s7, s7, s51
	v_lshl_add_u64 v[160:161], v[160:161], 0, s[26:27]
	s_mov_b32 m0, s7
	ds_read_b128 v[196:199], v178 offset:49152
	ds_read_b128 v[200:203], v178 offset:50176
	ds_read_b128 v[204:207], v178 offset:51200
	ds_read_b128 v[208:211], v178 offset:52224
	ds_read_b128 v[212:215], v178 offset:53248
	ds_read_b128 v[216:219], v178 offset:54272
	ds_read_b128 v[220:223], v178 offset:55296
	ds_read_b128 v[224:227], v178 offset:56320
	global_load_lds_dwordx4 v[160:161], off
	v_lshl_add_u64 v[160:161], v[228:229], 0, s[26:27]
	s_add_i32 m0, s7, 0x2000
	s_add_i32 s7, vcc_hi, s51
	global_load_lds_dwordx4 v[160:161], off
	v_lshl_add_u64 v[160:161], v[230:231], 0, s[26:27]
	s_mov_b32 m0, s7
	s_nop 0
	global_load_lds_dwordx4 v[160:161], off
	v_lshl_add_u64 v[160:161], v[232:233], 0, s[26:27]
	s_add_i32 m0, s7, 0x2000
	s_nop 0
	global_load_lds_dwordx4 v[160:161], off
	v_lshl_add_u64 v[160:161], v[234:235], 0, s[26:27]
	s_mov_b32 m0, s57
	s_nop 0
	global_load_lds_dwordx4 v[160:161], off
	v_lshl_add_u64 v[160:161], v[236:237], 0, s[26:27]
	s_mov_b32 m0, s58
	s_nop 0
	global_load_lds_dwordx4 v[160:161], off
	s_waitcnt vmcnt(8)
	s_waitcnt lgkmcnt(0)
	s_barrier
	s_waitcnt lgkmcnt(0)
	v_mfma_f32_16x16x32_bf16 v[60:63], v[128:131], v[196:199], v[60:63]
	v_mfma_f32_16x16x32_bf16 v[56:59], v[152:155], v[196:199], v[56:59]
	v_mfma_f32_16x16x32_bf16 v[44:47], v[128:131], v[204:207], v[44:47]
	v_mfma_f32_16x16x32_bf16 v[40:43], v[152:155], v[204:207], v[40:43]
	v_mfma_f32_16x16x32_bf16 v[28:31], v[128:131], v[212:215], v[28:31]
	v_mfma_f32_16x16x32_bf16 v[24:27], v[152:155], v[212:215], v[24:27]
	v_mfma_f32_16x16x32_bf16 v[12:15], v[128:131], v[220:223], v[12:15]
	v_mfma_f32_16x16x32_bf16 v[8:11], v[152:155], v[220:223], v[8:11]
	v_mfma_f32_16x16x32_bf16 v[60:63], v[132:135], v[200:203], v[60:63]
	v_mfma_f32_16x16x32_bf16 v[56:59], v[156:159], v[200:203], v[56:59]
	v_mfma_f32_16x16x32_bf16 v[44:47], v[132:135], v[208:211], v[44:47]
	v_mfma_f32_16x16x32_bf16 v[40:43], v[156:159], v[208:211], v[40:43]
	v_mfma_f32_16x16x32_bf16 v[28:31], v[132:135], v[216:219], v[28:31]
	v_mfma_f32_16x16x32_bf16 v[24:27], v[156:159], v[216:219], v[24:27]
	v_mfma_f32_16x16x32_bf16 v[12:15], v[132:135], v[224:227], v[12:15]
	v_mfma_f32_16x16x32_bf16 v[8:11], v[156:159], v[224:227], v[8:11]
	v_mfma_f32_16x16x32_bf16 v[52:55], v[180:183], v[196:199], v[52:55]
	v_mfma_f32_16x16x32_bf16 v[48:51], v[188:191], v[196:199], v[48:51]
	v_mfma_f32_16x16x32_bf16 v[36:39], v[180:183], v[204:207], v[36:39]
	v_mfma_f32_16x16x32_bf16 v[32:35], v[188:191], v[204:207], v[32:35]
	v_mfma_f32_16x16x32_bf16 v[20:23], v[180:183], v[212:215], v[20:23]
	v_mfma_f32_16x16x32_bf16 v[16:19], v[188:191], v[212:215], v[16:19]
	v_mfma_f32_16x16x32_bf16 v[4:7], v[180:183], v[220:223], v[4:7]
	v_mfma_f32_16x16x32_bf16 v[0:3], v[188:191], v[220:223], v[0:3]
	v_mfma_f32_16x16x32_bf16 v[52:55], v[184:187], v[200:203], v[52:55]
	v_mfma_f32_16x16x32_bf16 v[48:51], v[192:195], v[200:203], v[48:51]
	v_mfma_f32_16x16x32_bf16 v[36:39], v[184:187], v[208:211], v[36:39]
	v_mfma_f32_16x16x32_bf16 v[32:35], v[192:195], v[208:211], v[32:35]
	v_mfma_f32_16x16x32_bf16 v[20:23], v[184:187], v[216:219], v[20:23]
	v_mfma_f32_16x16x32_bf16 v[16:19], v[192:195], v[216:219], v[16:19]
	v_mfma_f32_16x16x32_bf16 v[4:7], v[184:187], v[224:227], v[4:7]
	v_mfma_f32_16x16x32_bf16 v[0:3], v[192:195], v[224:227], v[0:3]
	s_barrier
	s_add_u32 s92, s92, 0x100
	s_addc_u32 s93, s93, 0
	s_add_u32 s96, s96, 0x100
	s_addc_u32 s97, s97, 0
	s_cmp_ge_u32 vcc_lo, s19
	s_mov_b32 s94, vcc_lo
	s_cbranch_scc0 .LBB0_150
.Lkloop_done:
	s_setprio 0
	s_and_b64 vcc, exec, s[80:81]
	s_cbranch_vccz .LBB0_153
	s_barrier
